# LN row loop: next row's loads issued one row ahead (counted vmcnt)
# speedup vs baseline: 1.0775x; 1.0033x over previous
; DI u16* XB(const Params& p) { return (u16*)(PWS(p) + WS_XB); }
; DI u16* R16(const Params& p, bool last) { return last ? (u16*)(PWS(p) + WS_BIG + B_R16_LAST) : (u16*)launder((char*)p.out); }
; DI int otid() { int t = threadIdx.x; asm volatile("" : "+v"(t)); return t; }
; DI void phase_ln(const Params& p, const float* g, const float* b, bool final_ln) {
;   const int tid_ = otid(); const int lane = tid_ & 63, wave = tid_ >> 6;
;   float* X = (float*)launder((char*)p.out);
;   const u16* r16 = R16(p, final_ln);
;   u16* xb = XB(p);
;   float4 gg[4], bb[4];
; #pragma unroll
;   for (int i = 0; i < 4; ++i) { gg[i] = *(const float4*)(g + i * 256 + lane * 4); bb[i] = *(const float4*)(b + i * 256 + lane * 4); }
;   for (int row = blockIdx.x * 8 + wave; row < T; row += gridDim.x * 8) {
;     float* xr = X + (size_t)row * D;
;     float4 v[4];
;     float s = 0.f;
; #pragma unroll
;     for (int i = 0; i < 4; ++i) {
;       const unsigned long long raw = __builtin_nontemporal_load((const unsigned long long*)(r16 + (size_t)row * D + i * 256 + lane * 4));
.LBB0_790:
	v_ashrrev_i32_e32 v2, 6, v0
	v_readlane_b32 s0, v252, 7
	v_mov_b32 v3, v197
	v_mov_b32 v4, v198
	s_nop 0
	v_readfirstlane_b32 s16, v3
	v_add_u32_e32 v38, s0, v2
	s_mov_b32 s0, 0x8000
	v_readfirstlane_b32 s17, v4
	v_cmp_gt_i32_e32 vcc, s0, v38
	s_and_saveexec_b64 s[0:1], vcc
	s_cbranch_execz .LBB0_801
	s_and_b64 s[6:7], s[48:49], exec
	s_cselect_b32 s18, 0x1000, 0
	s_waitcnt lgkmcnt(0)
	s_add_u32 s6, s8, s18
	v_lshlrev_b32_e32 v0, 2, v0
	s_addc_u32 s7, s9, 0
	v_and_b32_e32 v34, 0xfc, v0
	s_add_u32 s8, s10, s18
	v_lshlrev_b32_e32 v0, 2, v34
	s_addc_u32 s9, s11, 0
	global_load_dwordx4 v[2:5], v0, s[6:7]
	global_load_dwordx4 v[6:9], v0, s[6:7] offset:1024
	global_load_dwordx4 v[10:13], v0, s[8:9]
	global_load_dwordx4 v[14:17], v0, s[8:9] offset:1024
	global_load_dwordx4 v[18:21], v0, s[6:7] offset:2048
	global_load_dwordx4 v[22:25], v0, s[6:7] offset:3072
	global_load_dwordx4 v[26:29], v0, s[8:9] offset:2048
	global_load_dwordx4 v[30:33], v0, s[8:9] offset:3072
	v_and_b32_e32 v36, 64, v207
	v_add_u32_e32 v36, 64, v36
	v_xor_b32_e32 v37, 32, v207
	v_cmp_lt_i32_e32 vcc, v37, v36
	v_lshlrev_b32_e32 v34, 1, v34
	v_mov_b32_e32 v35, v1
	v_cndmask_b32_e32 v37, v207, v37, vcc
	v_lshlrev_b32_e32 v64, 2, v37
	v_xor_b32_e32 v37, 16, v207
	v_cmp_lt_i32_e32 vcc, v37, v36
	v_lshl_add_u64 v[40:41], s[12:13], 0, v[34:35]
	v_lshl_add_u64 v[34:35], s[16:17], 0, v[34:35]
	v_cndmask_b32_e32 v37, v207, v37, vcc
	v_lshlrev_b32_e32 v65, 2, v37
	v_xor_b32_e32 v37, 8, v207
	v_cmp_lt_i32_e32 vcc, v37, v36
	s_mov_b64 s[6:7], 0x7b14c00
	v_lshl_add_u64 v[42:43], v[34:35], 0, s[6:7]
	v_cndmask_b32_e32 v37, v207, v37, vcc
	v_lshlrev_b32_e32 v66, 2, v37
	v_xor_b32_e32 v37, 4, v207
	v_cmp_lt_i32_e32 vcc, v37, v36
	v_lshl_add_u64 v[44:45], s[4:5], 0, v[0:1]
	s_mov_b64 s[4:5], 0
	v_cndmask_b32_e32 v37, v207, v37, vcc
	v_lshlrev_b32_e32 v67, 2, v37
	v_xor_b32_e32 v37, 2, v207
	v_cmp_lt_i32_e32 vcc, v37, v36
	s_nop 1
	v_cndmask_b32_e32 v37, v207, v37, vcc
	v_lshlrev_b32_e32 v68, 2, v37
	v_xor_b32_e32 v37, 1, v207
	v_cmp_lt_i32_e32 vcc, v37, v36
	s_nop 1
	v_cndmask_b32_e32 v36, v207, v37, vcc
	v_lshlrev_b32_e32 v69, 2, v36
	v_ashrrev_i32_e32 v39, 31, v38
	v_lshlrev_b64 v[88:89], 11, v[38:39]
	v_lshl_add_u64 v[88:89], v[40:41], 0, v[88:89]
	global_load_dwordx2 v[72:73], v[88:89], off nt
	global_load_dwordx2 v[74:75], v[88:89], off offset:512 nt
	global_load_dwordx2 v[76:77], v[88:89], off offset:1024 nt
	global_load_dwordx2 v[78:79], v[88:89], off offset:1536 nt
	s_waitcnt vmcnt(0)
	s_branch .LBB0_793

; DI void phase_ln(const Params& p, const float* g, const float* b, bool final_ln) {
;     ...
;   for (int row = blockIdx.x * 8 + wave; row < T; row += gridDim.x * 8) {
;     float* xr = X + (size_t)row * D;
;     float4 v[4];
;     float s = 0.f;
; #pragma unroll
;     for (int i = 0; i < 4; ++i) {
;       const unsigned long long raw = __builtin_nontemporal_load((const unsigned long long*)(r16 + (size_t)row * D + i * 256 + lane * 4));
;       v[i].x = (float)__builtin_bit_cast(_Float16, (u16)(raw & 0xffffu));
;       v[i].y = (float)__builtin_bit_cast(_Float16, (u16)((raw >> 16) & 0xffffu));
;       v[i].z = (float)__builtin_bit_cast(_Float16, (u16)((raw >> 32) & 0xffffu));
;       v[i].w = (float)__builtin_bit_cast(_Float16, (u16)(raw >> 48));
;       s += v[i].x + v[i].y + v[i].z + v[i].w;
;     }
;     const float mean = wave_sum(s) * (1.f / D);
;     float q = 0.f;
; #pragma unroll
;     for (int i = 0; i < 4; ++i) {
;       v[i].x -= mean; v[i].y -= mean; v[i].z -= mean; v[i].w -= mean;
;       q += v[i].x * v[i].x + v[i].y * v[i].y + v[i].z * v[i].z + v[i].w * v[i].w;
;     }
;     const float rstd = rsqrtf(wave_sum(q) * (1.f / D) + 1e-5f);
; #pragma unroll
;     for (int i = 0; i < 4; ++i) {
;       float4 o;
;       o.x = v[i].x * rstd * gg[i].x + bb[i].x; o.y = v[i].y * rstd * gg[i].y + bb[i].y;
;       o.z = v[i].z * rstd * gg[i].z + bb[i].z; o.w = v[i].w * rstd * gg[i].w + bb[i].w;
;       if (final_ln) *(float4*)(xr + i * 256 + lane * 4) = o;
.LBB0_793:
	s_waitcnt vmcnt(4)
	v_mov_b32_e32 v36, v72
	v_mov_b32_e32 v37, v73
	v_mov_b32_e32 v46, v74
	v_mov_b32_e32 v47, v75
	v_mov_b32_e32 v48, v76
	v_mov_b32_e32 v49, v77
	v_mov_b32_e32 v50, v78
	v_mov_b32_e32 v51, v79
	v_add_u32_e32 v88, s72, v38
	v_min_i32_e32 v88, 0x7fff, v88
	v_ashrrev_i32_e32 v89, 31, v88
	v_lshlrev_b64 v[88:89], 11, v[88:89]
	v_lshl_add_u64 v[88:89], v[40:41], 0, v[88:89]
	global_load_dwordx2 v[72:73], v[88:89], off nt
	global_load_dwordx2 v[74:75], v[88:89], off offset:512 nt
	global_load_dwordx2 v[76:77], v[88:89], off offset:1024 nt
	global_load_dwordx2 v[78:79], v[88:89], off offset:1536 nt
	v_cvt_f32_f16_e32 v62, v36
	v_cvt_f32_f16_sdwa v63, v36 dst_sel:DWORD dst_unused:UNUSED_PAD src0_sel:WORD_1
	v_cvt_f32_f16_e32 v56, v48
	v_cvt_f32_f16_e32 v52, v50
	v_cvt_f32_f16_sdwa v53, v50 dst_sel:DWORD dst_unused:UNUSED_PAD src0_sel:WORD_1
	v_cvt_f32_f16_sdwa v57, v48 dst_sel:DWORD dst_unused:UNUSED_PAD src0_sel:WORD_1
	v_cvt_f32_f16_e32 v34, v51
	v_cvt_f32_f16_e32 v54, v49
	v_cvt_f32_f16_sdwa v35, v51 dst_sel:DWORD dst_unused:UNUSED_PAD src0_sel:WORD_1
	v_cvt_f32_f16_sdwa v55, v49 dst_sel:DWORD dst_unused:UNUSED_PAD src0_sel:WORD_1
	v_mov_b32_e32 v48, v56
	v_mov_b32_e32 v49, v52
	v_mov_b32_e32 v50, v57
	v_mov_b32_e32 v51, v53
	v_pk_add_f32 v[48:49], v[48:49], v[50:51]
	v_mov_b32_e32 v50, v54
	v_mov_b32_e32 v51, v34
	v_pk_add_f32 v[48:49], v[48:49], v[50:51]
	v_mov_b32_e32 v50, v55
	v_mov_b32_e32 v51, v35
	v_pk_add_f32 v[48:49], v[48:49], v[50:51]
	v_cvt_f32_f16_e32 v50, v46
	v_cvt_f32_f16_sdwa v51, v46 dst_sel:DWORD dst_unused:UNUSED_PAD src0_sel:WORD_1
	v_cvt_f32_f16_e32 v58, v47
	v_cvt_f32_f16_e32 v60, v37
	v_cvt_f32_f16_sdwa v59, v47 dst_sel:DWORD dst_unused:UNUSED_PAD src0_sel:WORD_1
	v_cvt_f32_f16_sdwa v61, v37 dst_sel:DWORD dst_unused:UNUSED_PAD src0_sel:WORD_1
	v_mov_b32_e32 v36, v62
	v_mov_b32_e32 v37, v50
	v_mov_b32_e32 v70, v63
	v_mov_b32_e32 v71, v51
	v_pk_add_f32 v[36:37], v[36:37], v[70:71]
	v_mov_b32_e32 v70, v60
	v_mov_b32_e32 v71, v58
	v_pk_add_f32 v[36:37], v[36:37], v[70:71]
	v_mov_b32_e32 v70, v61
	v_mov_b32_e32 v71, v59
	v_pk_add_f32 v[36:37], v[36:37], v[70:71]
	v_lshlrev_b64 v[46:47], 12, v[38:39]
	v_add_f32_e32 v0, 0, v36
	v_add_f32_e32 v0, v0, v37
	v_add_f32_e32 v0, v0, v48
	v_add_f32_e32 v0, v0, v49
	ds_bpermute_b32 v36, v64, v0
	v_lshl_add_u64 v[46:47], v[44:45], 0, v[46:47]
	s_waitcnt lgkmcnt(0)
	v_add_f32_e32 v0, v0, v36
	ds_bpermute_b32 v36, v65, v0
	s_waitcnt lgkmcnt(0)
	v_add_f32_e32 v0, v0, v36
	ds_bpermute_b32 v36, v66, v0
	s_waitcnt lgkmcnt(0)
	v_add_f32_e32 v0, v0, v36
	ds_bpermute_b32 v36, v67, v0
	s_waitcnt lgkmcnt(0)
	v_add_f32_e32 v0, v0, v36
	ds_bpermute_b32 v36, v68, v0
	s_waitcnt lgkmcnt(0)
	v_add_f32_e32 v0, v0, v36
	ds_bpermute_b32 v36, v69, v0
	s_waitcnt lgkmcnt(0)
	v_add_f32_e32 v0, v0, v36
	v_mul_f32_e32 v0, 0x3a800000, v0
	v_pk_add_f32 v[36:37], v[62:63], v[0:1] op_sel_hi:[1,0] neg_lo:[0,1] neg_hi:[0,1]
	v_pk_add_f32 v[50:51], v[50:51], v[0:1] op_sel_hi:[1,0] neg_lo:[0,1] neg_hi:[0,1]
	v_pk_add_f32 v[62:63], v[60:61], v[0:1] op_sel_hi:[1,0] neg_lo:[0,1] neg_hi:[0,1]
	v_mov_b32_e32 v60, v37
	v_mov_b32_e32 v61, v51
	v_pk_add_f32 v[48:49], v[58:59], v[0:1] op_sel_hi:[1,0] neg_lo:[0,1] neg_hi:[0,1]
	v_mov_b32_e32 v58, v36
	v_mov_b32_e32 v59, v50
	v_pk_mul_f32 v[60:61], v[60:61], v[60:61]
	s_nop 0
	v_pk_fma_f32 v[58:59], v[58:59], v[58:59], v[60:61]
	v_mov_b32_e32 v60, v62
	v_mov_b32_e32 v61, v48
	v_pk_fma_f32 v[58:59], v[60:61], v[60:61], v[58:59]
	v_mov_b32_e32 v60, v63
	v_mov_b32_e32 v61, v49
	v_pk_fma_f32 v[60:61], v[60:61], v[60:61], v[58:59]
	v_pk_add_f32 v[58:59], v[56:57], v[0:1] op_sel_hi:[1,0] neg_lo:[0,1] neg_hi:[0,1]
	v_pk_add_f32 v[56:57], v[54:55], v[0:1] op_sel_hi:[1,0] neg_lo:[0,1] neg_hi:[0,1]
	v_pk_add_f32 v[54:55], v[52:53], v[0:1] op_sel_hi:[1,0] neg_lo:[0,1] neg_hi:[0,1]
	v_mov_b32_e32 v71, v59
	v_mov_b32_e32 v70, v55
	v_pk_add_f32 v[52:53], v[34:35], v[0:1] op_sel_hi:[1,0] neg_lo:[0,1] neg_hi:[0,1]
	v_mov_b32_e32 v34, v54
	v_mov_b32_e32 v35, v58
	v_pk_mul_f32 v[70:71], v[70:71], v[70:71]
	v_add_f32_e32 v0, v60, v61
	v_pk_fma_f32 v[34:35], v[34:35], v[34:35], v[70:71]
	v_mov_b32_e32 v70, v52
	v_mov_b32_e32 v71, v56
	v_pk_fma_f32 v[34:35], v[70:71], v[70:71], v[34:35]
	v_mov_b32_e32 v70, v53
	v_mov_b32_e32 v71, v57
	v_pk_fma_f32 v[34:35], v[70:71], v[70:71], v[34:35]
	s_nop 0
	v_add_f32_e32 v0, v35, v0
	v_add_f32_e32 v0, v34, v0
	ds_bpermute_b32 v34, v64, v0
	s_waitcnt lgkmcnt(0)
	v_add_f32_e32 v0, v0, v34
	ds_bpermute_b32 v34, v65, v0
	s_waitcnt lgkmcnt(0)
	v_add_f32_e32 v0, v0, v34
	ds_bpermute_b32 v34, v66, v0
	s_waitcnt lgkmcnt(0)
	v_add_f32_e32 v0, v0, v34
	ds_bpermute_b32 v34, v67, v0
	s_waitcnt lgkmcnt(0)
	v_add_f32_e32 v0, v0, v34
	ds_bpermute_b32 v34, v68, v0
	s_waitcnt lgkmcnt(0)
	v_add_f32_e32 v0, v0, v34
	ds_bpermute_b32 v34, v69, v0
	s_waitcnt lgkmcnt(0)
	v_add_f32_e32 v0, v0, v34
	v_fmamk_f32 v0, v0, 0x3a800000, v200
	v_cmp_gt_f32_e32 vcc, s19, v0
	v_mul_f32_e32 v34, 0x4b800000, v0
	s_nop 0
	v_cndmask_b32_e32 v0, v0, v34, vcc
	v_rsq_f32_e32 v0, v0
	s_nop 0
	v_mul_f32_e32 v34, 0x45800000, v0
	v_cndmask_b32_e32 v60, v0, v34, vcc
	v_pk_mul_f32 v[34:35], v[36:37], v[60:61] op_sel_hi:[1,0]
	v_pk_mul_f32 v[36:37], v[62:63], v[60:61] op_sel_hi:[1,0]
	v_cndmask_b32_e64 v0, 0, 1, s[14:15]
	v_pk_fma_f32 v[34:35], v[2:3], v[34:35], v[10:11]
	v_pk_fma_f32 v[36:37], v[4:5], v[36:37], v[12:13]
	v_cmp_ne_u32_e64 s[8:9], 1, v0
	s_andn2_b64 vcc, exec, s[14:15]
	s_cbranch_vccnz .LBB0_795
	global_store_dwordx4 v[46:47], v[34:37], off
